# v44 + P2 forget-gate scan: 32 serialized strided loads issued together with one wait
# speedup vs baseline: 1.0005x; 1.0005x over previous
; __device__ __forceinline__ float bf1(bf16_t h) { return __uint_as_float((unsigned)h << 16); }
; __global__ void __launch_bounds__(512, 2) mega_fwd(Args a) {
;     ...
;     for (int bh = gw; bh < NB * NH; bh += NGW) {
;         const int b = bh >> 3, hh = bh & 7; const float bfg = a.in[I_BFORGET][hh];
;         float lf[32]; float run = 0.f;
; #pragma unroll
;         for (int i = 0; i < 32; ++i) { const float f = bf1(PROJ[((size_t)b * SEQ + 32 * lane + i) * NPROJ + PC_FLOG + hh]) + bfg; run += -logf(1.0f + expf(-f)); lf[i] = run; }
.LBB0_892:
	s_ashr_i32 s16, s20, 3
	s_ashr_i32 s17, s16, 31
	s_lshl_b64 s[16:17], s[16:17], 11
	v_or_b32_e32 v8, s16, v0
	v_mad_u64_u32 v[8:9], s[40:41], v8, s3, v[6:7]
	v_mad_i32_i24 v9, s17, v2, v9
	v_lshl_add_u64 v[8:9], v[8:9], 0, s[24:25]
	v_add_co_u32_e32 v132, vcc, 0x3000, v8
	s_nop 1
	v_addc_co_u32_e32 v133, vcc, 0, v9, vcc
	global_load_ushort v100, v[132:133], off offset:1664
	v_add_co_u32_e32 v132, vcc, s36, v8
	s_nop 1
	v_addc_co_u32_e32 v133, vcc, 0, v9, vcc
	global_load_ushort v101, v[132:133], off offset:3712
	v_add_co_u32_e32 v132, vcc, s37, v8
	s_nop 1
	v_addc_co_u32_e32 v133, vcc, 0, v9, vcc
	global_load_ushort v102, v[132:133], off offset:1664
	v_add_co_u32_e32 v132, vcc, s38, v8
	s_nop 1
	v_addc_co_u32_e32 v133, vcc, 0, v9, vcc
	global_load_ushort v103, v[132:133], off offset:3712
	v_add_co_u32_e32 v132, vcc, s39, v8
	s_nop 1
	v_addc_co_u32_e32 v133, vcc, 0, v9, vcc
	global_load_ushort v104, v[132:133], off offset:1664
	v_add_co_u32_e32 v132, vcc, s42, v8
	s_nop 1
	v_addc_co_u32_e32 v133, vcc, 0, v9, vcc
	global_load_ushort v105, v[132:133], off offset:3712
	v_add_co_u32_e32 v132, vcc, s43, v8
	s_nop 1
	v_addc_co_u32_e32 v133, vcc, 0, v9, vcc
	global_load_ushort v106, v[132:133], off offset:1664
	v_add_co_u32_e32 v132, vcc, s53, v8
	s_nop 1
	v_addc_co_u32_e32 v133, vcc, 0, v9, vcc
	global_load_ushort v107, v[132:133], off offset:3712
	v_add_co_u32_e32 v132, vcc, s58, v8
	s_nop 1
	v_addc_co_u32_e32 v133, vcc, 0, v9, vcc
	global_load_ushort v108, v[132:133], off offset:1664
	v_add_co_u32_e32 v132, vcc, s59, v8
	s_nop 1
	v_addc_co_u32_e32 v133, vcc, 0, v9, vcc
	global_load_ushort v109, v[132:133], off offset:3712
	v_add_co_u32_e32 v132, vcc, s60, v8
	s_nop 1
	v_addc_co_u32_e32 v133, vcc, 0, v9, vcc
	global_load_ushort v110, v[132:133], off offset:1664
	v_add_co_u32_e32 v132, vcc, s61, v8
	s_nop 1
	v_addc_co_u32_e32 v133, vcc, 0, v9, vcc
	global_load_ushort v111, v[132:133], off offset:3712
	v_add_co_u32_e32 v132, vcc, s62, v8
	s_nop 1
	v_addc_co_u32_e32 v133, vcc, 0, v9, vcc
	global_load_ushort v112, v[132:133], off offset:1664
	v_add_co_u32_e32 v132, vcc, s63, v8
	s_nop 1
	v_addc_co_u32_e32 v133, vcc, 0, v9, vcc
	global_load_ushort v113, v[132:133], off offset:3712
	v_add_co_u32_e32 v132, vcc, s64, v8
	s_nop 1
	v_addc_co_u32_e32 v133, vcc, 0, v9, vcc
	global_load_ushort v114, v[132:133], off offset:1664
	v_add_co_u32_e32 v132, vcc, s65, v8
	s_nop 1
	v_addc_co_u32_e32 v133, vcc, 0, v9, vcc
	global_load_ushort v115, v[132:133], off offset:3712
	v_add_co_u32_e32 v132, vcc, s66, v8
	s_nop 1
	v_addc_co_u32_e32 v133, vcc, 0, v9, vcc
	global_load_ushort v116, v[132:133], off offset:1664
	v_add_co_u32_e32 v132, vcc, s67, v8
	s_nop 1
	v_addc_co_u32_e32 v133, vcc, 0, v9, vcc
	global_load_ushort v117, v[132:133], off offset:3712
	v_add_co_u32_e32 v132, vcc, s68, v8
	s_nop 1
	v_addc_co_u32_e32 v133, vcc, 0, v9, vcc
	global_load_ushort v118, v[132:133], off offset:1664
	v_add_co_u32_e32 v132, vcc, s69, v8
	s_nop 1
	v_addc_co_u32_e32 v133, vcc, 0, v9, vcc
	global_load_ushort v119, v[132:133], off offset:3712
	v_add_co_u32_e32 v132, vcc, s70, v8
	s_nop 1
	v_addc_co_u32_e32 v133, vcc, 0, v9, vcc
	global_load_ushort v120, v[132:133], off offset:1664
	v_add_co_u32_e32 v132, vcc, s71, v8
	s_nop 1
	v_addc_co_u32_e32 v133, vcc, 0, v9, vcc
	global_load_ushort v121, v[132:133], off offset:3712
	v_add_co_u32_e32 v132, vcc, s72, v8
	s_nop 1
	v_addc_co_u32_e32 v133, vcc, 0, v9, vcc
	global_load_ushort v122, v[132:133], off offset:1664
	v_add_co_u32_e32 v132, vcc, s73, v8
	s_nop 1
	v_addc_co_u32_e32 v133, vcc, 0, v9, vcc
	global_load_ushort v123, v[132:133], off offset:3712
	v_add_co_u32_e32 v132, vcc, s74, v8
	s_nop 1
	v_addc_co_u32_e32 v133, vcc, 0, v9, vcc
	global_load_ushort v124, v[132:133], off offset:1664
	v_add_co_u32_e32 v132, vcc, s75, v8
	s_nop 1
	v_addc_co_u32_e32 v133, vcc, 0, v9, vcc
	global_load_ushort v125, v[132:133], off offset:3712
	v_add_co_u32_e32 v132, vcc, s76, v8
	s_nop 1
	v_addc_co_u32_e32 v133, vcc, 0, v9, vcc
	global_load_ushort v126, v[132:133], off offset:1664
	v_add_co_u32_e32 v132, vcc, s77, v8
	s_nop 1
	v_addc_co_u32_e32 v133, vcc, 0, v9, vcc
	global_load_ushort v127, v[132:133], off offset:3712
	v_add_co_u32_e32 v132, vcc, s79, v8
	s_nop 1
	v_addc_co_u32_e32 v133, vcc, 0, v9, vcc
	global_load_ushort v128, v[132:133], off offset:1664
	v_add_co_u32_e32 v132, vcc, s80, v8
	s_nop 1
	v_addc_co_u32_e32 v133, vcc, 0, v9, vcc
	global_load_ushort v129, v[132:133], off offset:3712
	v_add_co_u32_e32 v132, vcc, s81, v8
	s_nop 1
	v_addc_co_u32_e32 v133, vcc, 0, v9, vcc
	global_load_ushort v130, v[132:133], off offset:1664
	v_add_co_u32_e32 v132, vcc, s82, v8
	s_nop 1
	v_addc_co_u32_e32 v133, vcc, 0, v9, vcc
	global_load_ushort v131, v[132:133], off offset:3712
	v_add_co_u32_e32 v18, vcc, 0x3000, v8
	global_load_dword v17, v3, s[26:27]
	s_nop 0
	v_addc_co_u32_e32 v19, vcc, 0, v9, vcc
	s_add_i32 s20, s20, s22
	s_cmpk_gt_i32 s20, 0x7f
	s_waitcnt vmcnt(0) lgkmcnt(0)
; __device__ __forceinline__ float bf1(bf16_t h) { return __uint_as_float((unsigned)h << 16); }
; __global__ void __launch_bounds__(512, 2) mega_fwd(Args a) {
;     ...
;         for (int i = 0; i < 32; ++i) { const float f = bf1(PROJ[((size_t)b * SEQ + 32 * lane + i) * NPROJ + PC_FLOG + hh]) + bfg; run += -logf(1.0f + expf(-f)); lf[i] = run; }
	v_mov_b32_e32 v18, v100
	v_lshlrev_b32_e32 v18, 16, v18
	v_add_f32_e32 v18, v17, v18
	v_mul_f32_e32 v19, 0xbfb8aa3b, v18
	v_fma_f32 v20, v18, s30, -v19
	v_rndne_f32_e32 v21, v19
	v_fmac_f32_e32 v20, 0xb2a5705f, v18
	v_sub_f32_e32 v19, v19, v21
	v_add_f32_e32 v19, v19, v20
	v_exp_f32_e32 v19, v19
	v_cvt_i32_f32_e32 v20, v21
	v_cmp_nlt_f32_e32 vcc, s21, v18
	v_ldexp_f32 v19, v19, v20
	s_nop 0
	v_cndmask_b32_e32 v19, 0, v19, vcc
	v_cmp_ngt_f32_e32 vcc, s23, v18
	s_nop 1
	v_cndmask_b32_e32 v18, v15, v19, vcc
	v_add_f32_e32 v18, 1.0, v18
	v_cmp_gt_f32_e32 vcc, s34, v18
	s_nop 1
	v_cndmask_b32_e64 v19, 0, 32, vcc
	v_ldexp_f32 v18, v18, v19
	v_log_f32_e32 v18, v18
	s_nop 0
	v_mul_f32_e32 v19, 0x3f317217, v18
	v_fma_f32 v19, v18, s35, -v19
	v_fmac_f32_e32 v19, 0x3377d1cf, v18
	v_fmac_f32_e32 v19, 0x3f317217, v18
	v_cmp_lt_f32_e64 s[16:17], |v18|, s31
	s_nop 1
	v_cndmask_b32_e64 v18, v18, v19, s[16:17]
	v_cndmask_b32_e32 v19, 0, v16, vcc
	v_add_co_u32_e32 v20, vcc, s36, v8
	v_sub_f32_e32 v18, v18, v19
	s_nop 0
	v_addc_co_u32_e32 v21, vcc, 0, v9, vcc
	v_mov_b32_e32 v19, v101
	v_lshlrev_b32_e32 v19, 16, v19
	v_add_f32_e32 v19, v17, v19
	v_mul_f32_e32 v20, 0xbfb8aa3b, v19
	v_fma_f32 v21, v19, s30, -v20
	v_rndne_f32_e32 v22, v20
	v_fmac_f32_e32 v21, 0xb2a5705f, v19
	v_sub_f32_e32 v20, v20, v22
	v_add_f32_e32 v20, v20, v21
	v_exp_f32_e32 v20, v20
	v_cvt_i32_f32_e32 v21, v22
	v_cmp_nlt_f32_e32 vcc, s21, v19
	v_ldexp_f32 v20, v20, v21
	s_nop 0
	v_cndmask_b32_e32 v20, 0, v20, vcc
	v_cmp_ngt_f32_e32 vcc, s23, v19
	s_nop 1
	v_cndmask_b32_e32 v19, v15, v20, vcc
	v_add_f32_e32 v19, 1.0, v19
	v_cmp_gt_f32_e32 vcc, s34, v19
	s_nop 1
	v_cndmask_b32_e64 v20, 0, 32, vcc
	v_ldexp_f32 v19, v19, v20
	v_log_f32_e32 v19, v19
	s_nop 0
	v_mul_f32_e32 v20, 0x3f317217, v19
	v_fma_f32 v20, v19, s35, -v20
	v_fmac_f32_e32 v20, 0x3377d1cf, v19
	v_fmac_f32_e32 v20, 0x3f317217, v19
	v_cmp_lt_f32_e64 s[16:17], |v19|, s31
	s_nop 1
	v_cndmask_b32_e64 v19, v19, v20, s[16:17]
	v_cndmask_b32_e32 v20, 0, v16, vcc
	v_sub_f32_e32 v19, v19, v20
	v_add_co_u32_e32 v20, vcc, s37, v8
	s_nop 1
	v_addc_co_u32_e32 v21, vcc, 0, v9, vcc
	v_mov_b32_e32 v20, v102
	v_lshlrev_b32_e32 v20, 16, v20
	v_add_f32_e32 v20, v17, v20
	v_mul_f32_e32 v21, 0xbfb8aa3b, v20
	v_fma_f32 v22, v20, s30, -v21
	v_rndne_f32_e32 v23, v21
	v_fmac_f32_e32 v22, 0xb2a5705f, v20
	v_sub_f32_e32 v21, v21, v23
	v_add_f32_e32 v21, v21, v22
	v_exp_f32_e32 v21, v21
	v_cvt_i32_f32_e32 v22, v23
	v_cmp_nlt_f32_e32 vcc, s21, v20
	v_ldexp_f32 v21, v21, v22
	s_nop 0
	v_cndmask_b32_e32 v21, 0, v21, vcc
	v_cmp_ngt_f32_e32 vcc, s23, v20
	s_nop 1
	v_cndmask_b32_e32 v20, v15, v21, vcc
	v_add_f32_e32 v20, 1.0, v20
	v_cmp_gt_f32_e32 vcc, s34, v20
	s_nop 1
	v_cndmask_b32_e64 v21, 0, 32, vcc
	v_ldexp_f32 v20, v20, v21
	v_log_f32_e32 v20, v20
	s_nop 0
	v_mul_f32_e32 v21, 0x3f317217, v20
	v_fma_f32 v21, v20, s35, -v21
	v_fmac_f32_e32 v21, 0x3377d1cf, v20
	v_fmac_f32_e32 v21, 0x3f317217, v20
	v_cmp_lt_f32_e64 s[16:17], |v20|, s31
	s_nop 1
	v_cndmask_b32_e64 v20, v20, v21, s[16:17]
	v_cndmask_b32_e32 v21, 0, v16, vcc
	v_add_co_u32_e32 v22, vcc, s38, v8
	v_sub_f32_e32 v20, v20, v21
	s_nop 0
	v_addc_co_u32_e32 v23, vcc, 0, v9, vcc
	v_mov_b32_e32 v21, v103
	v_lshlrev_b32_e32 v21, 16, v21
	v_add_f32_e32 v21, v17, v21
	v_mul_f32_e32 v22, 0xbfb8aa3b, v21
	v_fma_f32 v23, v21, s30, -v22
	v_rndne_f32_e32 v24, v22
	v_fmac_f32_e32 v23, 0xb2a5705f, v21
	v_sub_f32_e32 v22, v22, v24
	v_add_f32_e32 v22, v22, v23
	v_exp_f32_e32 v22, v22
	v_cvt_i32_f32_e32 v23, v24
	v_cmp_nlt_f32_e32 vcc, s21, v21
	v_ldexp_f32 v22, v22, v23
	s_nop 0
	v_cndmask_b32_e32 v22, 0, v22, vcc
	v_cmp_ngt_f32_e32 vcc, s23, v21
	s_nop 1
	v_cndmask_b32_e32 v21, v15, v22, vcc
	v_add_f32_e32 v21, 1.0, v21
	v_cmp_gt_f32_e32 vcc, s34, v21
	s_nop 1
	v_cndmask_b32_e64 v22, 0, 32, vcc
	v_ldexp_f32 v21, v21, v22
	v_log_f32_e32 v21, v21
	s_nop 0
	v_mul_f32_e32 v22, 0x3f317217, v21
	v_fma_f32 v22, v21, s35, -v22
	v_fmac_f32_e32 v22, 0x3377d1cf, v21
	v_fmac_f32_e32 v22, 0x3f317217, v21
	v_cmp_lt_f32_e64 s[16:17], |v21|, s31
	s_nop 1
	v_cndmask_b32_e64 v21, v21, v22, s[16:17]
	v_cndmask_b32_e32 v22, 0, v16, vcc
	v_sub_f32_e32 v21, v21, v22
	v_add_co_u32_e32 v22, vcc, s39, v8
	s_nop 1
	v_addc_co_u32_e32 v23, vcc, 0, v9, vcc
	v_mov_b32_e32 v22, v104
	v_lshlrev_b32_e32 v22, 16, v22
	v_add_f32_e32 v22, v17, v22
	v_mul_f32_e32 v23, 0xbfb8aa3b, v22
	v_fma_f32 v24, v22, s30, -v23
	v_rndne_f32_e32 v25, v23
	v_fmac_f32_e32 v24, 0xb2a5705f, v22
	v_sub_f32_e32 v23, v23, v25
	v_add_f32_e32 v23, v23, v24
	v_exp_f32_e32 v23, v23
	v_cvt_i32_f32_e32 v24, v25
	v_cmp_nlt_f32_e32 vcc, s21, v22
	v_ldexp_f32 v23, v23, v24
	s_nop 0
	v_cndmask_b32_e32 v23, 0, v23, vcc
	v_cmp_ngt_f32_e32 vcc, s23, v22
	s_nop 1
	v_cndmask_b32_e32 v22, v15, v23, vcc
	v_add_f32_e32 v22, 1.0, v22
	v_cmp_gt_f32_e32 vcc, s34, v22
	s_nop 1
	v_cndmask_b32_e64 v23, 0, 32, vcc
	v_ldexp_f32 v22, v22, v23
	v_log_f32_e32 v22, v22
	s_nop 0
	v_mul_f32_e32 v23, 0x3f317217, v22
	v_fma_f32 v23, v22, s35, -v23
	v_fmac_f32_e32 v23, 0x3377d1cf, v22
	v_fmac_f32_e32 v23, 0x3f317217, v22
	v_cmp_lt_f32_e64 s[16:17], |v22|, s31
	s_nop 1
	v_cndmask_b32_e64 v22, v22, v23, s[16:17]
	v_cndmask_b32_e32 v23, 0, v16, vcc
	v_add_co_u32_e32 v24, vcc, s42, v8
	v_sub_f32_e32 v22, v22, v23
	s_nop 0
	v_addc_co_u32_e32 v25, vcc, 0, v9, vcc
	v_mov_b32_e32 v23, v105
	v_lshlrev_b32_e32 v23, 16, v23
	v_add_f32_e32 v23, v17, v23
	v_mul_f32_e32 v24, 0xbfb8aa3b, v23
	v_fma_f32 v25, v23, s30, -v24
	v_rndne_f32_e32 v26, v24
	v_fmac_f32_e32 v25, 0xb2a5705f, v23
	v_sub_f32_e32 v24, v24, v26
	v_add_f32_e32 v24, v24, v25
	v_exp_f32_e32 v24, v24
	v_cvt_i32_f32_e32 v25, v26
	v_cmp_nlt_f32_e32 vcc, s21, v23
; __device__ __forceinline__ float bf1(bf16_t h) { return __uint_as_float((unsigned)h << 16); }
; __global__ void __launch_bounds__(512, 2) mega_fwd(Args a) {
;     ...
;         for (int i = 0; i < 32; ++i) { const float f = bf1(PROJ[((size_t)b * SEQ + 32 * lane + i) * NPROJ + PC_FLOG + hh]) + bfg; run += -logf(1.0f + expf(-f)); lf[i] = run; }
	v_ldexp_f32 v24, v24, v25
	s_nop 0
	v_cndmask_b32_e32 v24, 0, v24, vcc
	v_cmp_ngt_f32_e32 vcc, s23, v23
	s_nop 1
	v_cndmask_b32_e32 v23, v15, v24, vcc
	v_add_f32_e32 v23, 1.0, v23
	v_cmp_gt_f32_e32 vcc, s34, v23
	s_nop 1
	v_cndmask_b32_e64 v24, 0, 32, vcc
	v_ldexp_f32 v23, v23, v24
	v_log_f32_e32 v23, v23
	s_nop 0
	v_mul_f32_e32 v24, 0x3f317217, v23
	v_fma_f32 v24, v23, s35, -v24
	v_fmac_f32_e32 v24, 0x3377d1cf, v23
	v_fmac_f32_e32 v24, 0x3f317217, v23
	v_cmp_lt_f32_e64 s[16:17], |v23|, s31
	s_nop 1
	v_cndmask_b32_e64 v23, v23, v24, s[16:17]
	v_cndmask_b32_e32 v24, 0, v16, vcc
	v_sub_f32_e32 v23, v23, v24
	v_add_co_u32_e32 v24, vcc, s43, v8
	s_nop 1
	v_addc_co_u32_e32 v25, vcc, 0, v9, vcc
	v_mov_b32_e32 v24, v106
	v_lshlrev_b32_e32 v24, 16, v24
	v_add_f32_e32 v24, v17, v24
	v_mul_f32_e32 v25, 0xbfb8aa3b, v24
	v_fma_f32 v26, v24, s30, -v25
	v_rndne_f32_e32 v27, v25
	v_fmac_f32_e32 v26, 0xb2a5705f, v24
	v_sub_f32_e32 v25, v25, v27
	v_add_f32_e32 v25, v25, v26
	v_exp_f32_e32 v25, v25
	v_cvt_i32_f32_e32 v26, v27
	v_cmp_nlt_f32_e32 vcc, s21, v24
	v_ldexp_f32 v25, v25, v26
	s_nop 0
	v_cndmask_b32_e32 v25, 0, v25, vcc
	v_cmp_ngt_f32_e32 vcc, s23, v24
	s_nop 1
	v_cndmask_b32_e32 v24, v15, v25, vcc
	v_add_f32_e32 v24, 1.0, v24
	v_cmp_gt_f32_e32 vcc, s34, v24
	s_nop 1
	v_cndmask_b32_e64 v25, 0, 32, vcc
	v_ldexp_f32 v24, v24, v25
	v_log_f32_e32 v24, v24
	s_nop 0
	v_mul_f32_e32 v25, 0x3f317217, v24
	v_fma_f32 v25, v24, s35, -v25
	v_fmac_f32_e32 v25, 0x3377d1cf, v24
	v_fmac_f32_e32 v25, 0x3f317217, v24
	v_cmp_lt_f32_e64 s[16:17], |v24|, s31
	s_nop 1
	v_cndmask_b32_e64 v24, v24, v25, s[16:17]
	v_cndmask_b32_e32 v25, 0, v16, vcc
	v_add_co_u32_e32 v26, vcc, s53, v8
	v_sub_f32_e32 v24, v24, v25
	s_nop 0
	v_addc_co_u32_e32 v27, vcc, 0, v9, vcc
	v_mov_b32_e32 v25, v107
	v_lshlrev_b32_e32 v25, 16, v25
	v_add_f32_e32 v25, v17, v25
	v_mul_f32_e32 v26, 0xbfb8aa3b, v25
	v_fma_f32 v27, v25, s30, -v26
	v_rndne_f32_e32 v28, v26
	v_fmac_f32_e32 v27, 0xb2a5705f, v25
	v_sub_f32_e32 v26, v26, v28
	v_add_f32_e32 v26, v26, v27
	v_exp_f32_e32 v26, v26
	v_cvt_i32_f32_e32 v27, v28
	v_cmp_nlt_f32_e32 vcc, s21, v25
	v_ldexp_f32 v26, v26, v27
	s_nop 0
	v_cndmask_b32_e32 v26, 0, v26, vcc
	v_cmp_ngt_f32_e32 vcc, s23, v25
	s_nop 1
	v_cndmask_b32_e32 v25, v15, v26, vcc
	v_add_f32_e32 v25, 1.0, v25
	v_cmp_gt_f32_e32 vcc, s34, v25
	s_nop 1
	v_cndmask_b32_e64 v26, 0, 32, vcc
	v_ldexp_f32 v25, v25, v26
	v_log_f32_e32 v25, v25
	s_nop 0
	v_mul_f32_e32 v26, 0x3f317217, v25
	v_fma_f32 v26, v25, s35, -v26
	v_fmac_f32_e32 v26, 0x3377d1cf, v25
	v_fmac_f32_e32 v26, 0x3f317217, v25
	v_cmp_lt_f32_e64 s[16:17], |v25|, s31
	s_nop 1
	v_cndmask_b32_e64 v25, v25, v26, s[16:17]
	v_cndmask_b32_e32 v26, 0, v16, vcc
	v_sub_f32_e32 v25, v25, v26
	v_add_co_u32_e32 v26, vcc, s58, v8
	s_nop 1
	v_addc_co_u32_e32 v27, vcc, 0, v9, vcc
	v_mov_b32_e32 v26, v108
	v_lshlrev_b32_e32 v26, 16, v26
	v_add_f32_e32 v26, v17, v26
	v_mul_f32_e32 v27, 0xbfb8aa3b, v26
	v_fma_f32 v28, v26, s30, -v27
	v_rndne_f32_e32 v29, v27
	v_fmac_f32_e32 v28, 0xb2a5705f, v26
	v_sub_f32_e32 v27, v27, v29
	v_add_f32_e32 v27, v27, v28
	v_exp_f32_e32 v27, v27
	v_cvt_i32_f32_e32 v28, v29
	v_cmp_nlt_f32_e32 vcc, s21, v26
	v_ldexp_f32 v27, v27, v28
	s_nop 0
	v_cndmask_b32_e32 v27, 0, v27, vcc
	v_cmp_ngt_f32_e32 vcc, s23, v26
	s_nop 1
	v_cndmask_b32_e32 v26, v15, v27, vcc
	v_add_f32_e32 v26, 1.0, v26
	v_cmp_gt_f32_e32 vcc, s34, v26
	s_nop 1
	v_cndmask_b32_e64 v27, 0, 32, vcc
	v_ldexp_f32 v26, v26, v27
	v_log_f32_e32 v26, v26
	s_nop 0
	v_mul_f32_e32 v27, 0x3f317217, v26
	v_fma_f32 v27, v26, s35, -v27
	v_fmac_f32_e32 v27, 0x3377d1cf, v26
	v_fmac_f32_e32 v27, 0x3f317217, v26
	v_cmp_lt_f32_e64 s[16:17], |v26|, s31
	s_nop 1
	v_cndmask_b32_e64 v26, v26, v27, s[16:17]
	v_cndmask_b32_e32 v27, 0, v16, vcc
	v_add_co_u32_e32 v28, vcc, s59, v8
	v_sub_f32_e32 v26, v26, v27
	s_nop 0
	v_addc_co_u32_e32 v29, vcc, 0, v9, vcc
	v_mov_b32_e32 v27, v109
	v_lshlrev_b32_e32 v27, 16, v27
	v_add_f32_e32 v27, v17, v27
	v_mul_f32_e32 v28, 0xbfb8aa3b, v27
	v_fma_f32 v29, v27, s30, -v28
	v_rndne_f32_e32 v30, v28
	v_fmac_f32_e32 v29, 0xb2a5705f, v27
	v_sub_f32_e32 v28, v28, v30
	v_add_f32_e32 v28, v28, v29
	v_exp_f32_e32 v28, v28
	v_cvt_i32_f32_e32 v29, v30
	v_cmp_nlt_f32_e32 vcc, s21, v27
	v_ldexp_f32 v28, v28, v29
	s_nop 0
	v_cndmask_b32_e32 v28, 0, v28, vcc
	v_cmp_ngt_f32_e32 vcc, s23, v27
	s_nop 1
	v_cndmask_b32_e32 v27, v15, v28, vcc
	v_add_f32_e32 v27, 1.0, v27
	v_cmp_gt_f32_e32 vcc, s34, v27
	s_nop 1
	v_cndmask_b32_e64 v28, 0, 32, vcc
	v_ldexp_f32 v27, v27, v28
	v_log_f32_e32 v27, v27
	s_nop 0
	v_mul_f32_e32 v28, 0x3f317217, v27
	v_fma_f32 v28, v27, s35, -v28
	v_fmac_f32_e32 v28, 0x3377d1cf, v27
	v_fmac_f32_e32 v28, 0x3f317217, v27
	v_cmp_lt_f32_e64 s[16:17], |v27|, s31
	s_nop 1
	v_cndmask_b32_e64 v27, v27, v28, s[16:17]
	v_cndmask_b32_e32 v28, 0, v16, vcc
	v_sub_f32_e32 v27, v27, v28
	v_add_co_u32_e32 v28, vcc, s60, v8
	s_nop 1
	v_addc_co_u32_e32 v29, vcc, 0, v9, vcc
	v_mov_b32_e32 v28, v110
	v_lshlrev_b32_e32 v28, 16, v28
	v_add_f32_e32 v28, v17, v28
	v_mul_f32_e32 v29, 0xbfb8aa3b, v28
	v_fma_f32 v30, v28, s30, -v29
	v_rndne_f32_e32 v31, v29
	v_fmac_f32_e32 v30, 0xb2a5705f, v28
	v_sub_f32_e32 v29, v29, v31
	v_add_f32_e32 v29, v29, v30
	v_exp_f32_e32 v29, v29
	v_cvt_i32_f32_e32 v30, v31
	v_cmp_nlt_f32_e32 vcc, s21, v28
	v_ldexp_f32 v29, v29, v30
	s_nop 0
	v_cndmask_b32_e32 v29, 0, v29, vcc
	v_cmp_ngt_f32_e32 vcc, s23, v28
	s_nop 1
	v_cndmask_b32_e32 v28, v15, v29, vcc
	v_add_f32_e32 v28, 1.0, v28
	v_cmp_gt_f32_e32 vcc, s34, v28
	s_nop 1
	v_cndmask_b32_e64 v29, 0, 32, vcc
	v_ldexp_f32 v28, v28, v29
	v_log_f32_e32 v28, v28
	s_nop 0
	v_mul_f32_e32 v29, 0x3f317217, v28
; __device__ __forceinline__ float bf1(bf16_t h) { return __uint_as_float((unsigned)h << 16); }
; __global__ void __launch_bounds__(512, 2) mega_fwd(Args a) {
;     ...
;         for (int i = 0; i < 32; ++i) { const float f = bf1(PROJ[((size_t)b * SEQ + 32 * lane + i) * NPROJ + PC_FLOG + hh]) + bfg; run += -logf(1.0f + expf(-f)); lf[i] = run; }
	v_fma_f32 v29, v28, s35, -v29
	v_fmac_f32_e32 v29, 0x3377d1cf, v28
	v_fmac_f32_e32 v29, 0x3f317217, v28
	v_cmp_lt_f32_e64 s[16:17], |v28|, s31
	s_nop 1
	v_cndmask_b32_e64 v28, v28, v29, s[16:17]
	v_cndmask_b32_e32 v29, 0, v16, vcc
	v_add_co_u32_e32 v30, vcc, s61, v8
	v_sub_f32_e32 v28, v28, v29
	s_nop 0
	v_addc_co_u32_e32 v31, vcc, 0, v9, vcc
	v_mov_b32_e32 v29, v111
	v_lshlrev_b32_e32 v29, 16, v29
	v_add_f32_e32 v29, v17, v29
	v_mul_f32_e32 v30, 0xbfb8aa3b, v29
	v_fma_f32 v31, v29, s30, -v30
	v_rndne_f32_e32 v32, v30
	v_fmac_f32_e32 v31, 0xb2a5705f, v29
	v_sub_f32_e32 v30, v30, v32
	v_add_f32_e32 v30, v30, v31
	v_exp_f32_e32 v30, v30
	v_cvt_i32_f32_e32 v31, v32
	v_cmp_nlt_f32_e32 vcc, s21, v29
	v_ldexp_f32 v30, v30, v31
	s_nop 0
	v_cndmask_b32_e32 v30, 0, v30, vcc
	v_cmp_ngt_f32_e32 vcc, s23, v29
	s_nop 1
	v_cndmask_b32_e32 v29, v15, v30, vcc
	v_add_f32_e32 v29, 1.0, v29
	v_cmp_gt_f32_e32 vcc, s34, v29
	s_nop 1
	v_cndmask_b32_e64 v30, 0, 32, vcc
	v_ldexp_f32 v29, v29, v30
	v_log_f32_e32 v29, v29
	s_nop 0
	v_mul_f32_e32 v30, 0x3f317217, v29
	v_fma_f32 v30, v29, s35, -v30
	v_fmac_f32_e32 v30, 0x3377d1cf, v29
	v_fmac_f32_e32 v30, 0x3f317217, v29
	v_cmp_lt_f32_e64 s[16:17], |v29|, s31
	s_nop 1
	v_cndmask_b32_e64 v29, v29, v30, s[16:17]
	v_cndmask_b32_e32 v30, 0, v16, vcc
	v_sub_f32_e32 v29, v29, v30
	v_add_co_u32_e32 v30, vcc, s62, v8
	s_nop 1
	v_addc_co_u32_e32 v31, vcc, 0, v9, vcc
	v_mov_b32_e32 v30, v112
	v_lshlrev_b32_e32 v30, 16, v30
	v_add_f32_e32 v30, v17, v30
	v_mul_f32_e32 v31, 0xbfb8aa3b, v30
	v_fma_f32 v32, v30, s30, -v31
	v_rndne_f32_e32 v33, v31
	v_fmac_f32_e32 v32, 0xb2a5705f, v30
	v_sub_f32_e32 v31, v31, v33
	v_add_f32_e32 v31, v31, v32
	v_exp_f32_e32 v31, v31
	v_cvt_i32_f32_e32 v32, v33
	v_cmp_nlt_f32_e32 vcc, s21, v30
	v_ldexp_f32 v31, v31, v32
	s_nop 0
	v_cndmask_b32_e32 v31, 0, v31, vcc
	v_cmp_ngt_f32_e32 vcc, s23, v30
	s_nop 1
	v_cndmask_b32_e32 v30, v15, v31, vcc
	v_add_f32_e32 v30, 1.0, v30
	v_cmp_gt_f32_e32 vcc, s34, v30
	s_nop 1
	v_cndmask_b32_e64 v31, 0, 32, vcc
	v_ldexp_f32 v30, v30, v31
	v_log_f32_e32 v30, v30
	s_nop 0
	v_mul_f32_e32 v31, 0x3f317217, v30
	v_fma_f32 v31, v30, s35, -v31
	v_fmac_f32_e32 v31, 0x3377d1cf, v30
	v_fmac_f32_e32 v31, 0x3f317217, v30
	v_cmp_lt_f32_e64 s[16:17], |v30|, s31
	s_nop 1
	v_cndmask_b32_e64 v30, v30, v31, s[16:17]
	v_cndmask_b32_e32 v31, 0, v16, vcc
	v_add_co_u32_e32 v32, vcc, s63, v8
	v_sub_f32_e32 v30, v30, v31
	s_nop 0
	v_addc_co_u32_e32 v33, vcc, 0, v9, vcc
	v_mov_b32_e32 v31, v113
	v_lshlrev_b32_e32 v31, 16, v31
	v_add_f32_e32 v31, v17, v31
	v_mul_f32_e32 v32, 0xbfb8aa3b, v31
	v_fma_f32 v33, v31, s30, -v32
	v_rndne_f32_e32 v34, v32
	v_fmac_f32_e32 v33, 0xb2a5705f, v31
	v_sub_f32_e32 v32, v32, v34
	v_add_f32_e32 v32, v32, v33
	v_exp_f32_e32 v32, v32
	v_cvt_i32_f32_e32 v33, v34
	v_cmp_nlt_f32_e32 vcc, s21, v31
	v_ldexp_f32 v32, v32, v33
	s_nop 0
	v_cndmask_b32_e32 v32, 0, v32, vcc
	v_cmp_ngt_f32_e32 vcc, s23, v31
	s_nop 1
	v_cndmask_b32_e32 v31, v15, v32, vcc
	v_add_f32_e32 v31, 1.0, v31
	v_cmp_gt_f32_e32 vcc, s34, v31
	s_nop 1
	v_cndmask_b32_e64 v32, 0, 32, vcc
	v_ldexp_f32 v31, v31, v32
	v_log_f32_e32 v31, v31
	s_nop 0
	v_mul_f32_e32 v32, 0x3f317217, v31
	v_fma_f32 v32, v31, s35, -v32
	v_fmac_f32_e32 v32, 0x3377d1cf, v31
	v_fmac_f32_e32 v32, 0x3f317217, v31
	v_cmp_lt_f32_e64 s[16:17], |v31|, s31
	s_nop 1
	v_cndmask_b32_e64 v31, v31, v32, s[16:17]
	v_cndmask_b32_e32 v32, 0, v16, vcc
	v_sub_f32_e32 v31, v31, v32
	v_add_co_u32_e32 v32, vcc, s64, v8
	s_nop 1
	v_addc_co_u32_e32 v33, vcc, 0, v9, vcc
	v_mov_b32_e32 v32, v114
	v_lshlrev_b32_e32 v32, 16, v32
	v_add_f32_e32 v32, v17, v32
	v_mul_f32_e32 v33, 0xbfb8aa3b, v32
	v_fma_f32 v34, v32, s30, -v33
	v_rndne_f32_e32 v35, v33
	v_fmac_f32_e32 v34, 0xb2a5705f, v32
	v_sub_f32_e32 v33, v33, v35
	v_add_f32_e32 v33, v33, v34
	v_exp_f32_e32 v33, v33
	v_cvt_i32_f32_e32 v34, v35
	v_cmp_nlt_f32_e32 vcc, s21, v32
	v_ldexp_f32 v33, v33, v34
	s_nop 0
	v_cndmask_b32_e32 v33, 0, v33, vcc
	v_cmp_ngt_f32_e32 vcc, s23, v32
	s_nop 1
	v_cndmask_b32_e32 v32, v15, v33, vcc
	v_add_f32_e32 v32, 1.0, v32
	v_cmp_gt_f32_e32 vcc, s34, v32
	s_nop 1
	v_cndmask_b32_e64 v33, 0, 32, vcc
	v_ldexp_f32 v32, v32, v33
	v_log_f32_e32 v32, v32
	s_nop 0
	v_mul_f32_e32 v33, 0x3f317217, v32
	v_fma_f32 v33, v32, s35, -v33
	v_fmac_f32_e32 v33, 0x3377d1cf, v32
	v_fmac_f32_e32 v33, 0x3f317217, v32
	v_cmp_lt_f32_e64 s[16:17], |v32|, s31
	s_nop 1
	v_cndmask_b32_e64 v32, v32, v33, s[16:17]
	v_cndmask_b32_e32 v33, 0, v16, vcc
	v_add_co_u32_e32 v34, vcc, s65, v8
	v_sub_f32_e32 v32, v32, v33
	s_nop 0
	v_addc_co_u32_e32 v35, vcc, 0, v9, vcc
	v_mov_b32_e32 v33, v115
	v_lshlrev_b32_e32 v33, 16, v33
	v_add_f32_e32 v33, v17, v33
	v_mul_f32_e32 v34, 0xbfb8aa3b, v33
	v_fma_f32 v35, v33, s30, -v34
	v_rndne_f32_e32 v36, v34
	v_fmac_f32_e32 v35, 0xb2a5705f, v33
	v_sub_f32_e32 v34, v34, v36
	v_add_f32_e32 v34, v34, v35
	v_exp_f32_e32 v34, v34
	v_cvt_i32_f32_e32 v35, v36
	v_cmp_nlt_f32_e32 vcc, s21, v33
	v_ldexp_f32 v34, v34, v35
	s_nop 0
	v_cndmask_b32_e32 v34, 0, v34, vcc
	v_cmp_ngt_f32_e32 vcc, s23, v33
	s_nop 1
	v_cndmask_b32_e32 v33, v15, v34, vcc
	v_add_f32_e32 v33, 1.0, v33
	v_cmp_gt_f32_e32 vcc, s34, v33
	s_nop 1
	v_cndmask_b32_e64 v34, 0, 32, vcc
	v_ldexp_f32 v33, v33, v34
	v_log_f32_e32 v33, v33
	s_nop 0
	v_mul_f32_e32 v34, 0x3f317217, v33
	v_fma_f32 v34, v33, s35, -v34
	v_fmac_f32_e32 v34, 0x3377d1cf, v33
	v_fmac_f32_e32 v34, 0x3f317217, v33
	v_cmp_lt_f32_e64 s[16:17], |v33|, s31
	s_nop 1
	v_cndmask_b32_e64 v33, v33, v34, s[16:17]
	v_cndmask_b32_e32 v34, 0, v16, vcc
	v_sub_f32_e32 v33, v33, v34
	v_add_co_u32_e32 v34, vcc, s66, v8
	s_nop 1
	v_addc_co_u32_e32 v35, vcc, 0, v9, vcc
; __device__ __forceinline__ float bf1(bf16_t h) { return __uint_as_float((unsigned)h << 16); }
; __global__ void __launch_bounds__(512, 2) mega_fwd(Args a) {
;     ...
;         for (int i = 0; i < 32; ++i) { const float f = bf1(PROJ[((size_t)b * SEQ + 32 * lane + i) * NPROJ + PC_FLOG + hh]) + bfg; run += -logf(1.0f + expf(-f)); lf[i] = run; }
	v_mov_b32_e32 v34, v116
	v_lshlrev_b32_e32 v34, 16, v34
	v_add_f32_e32 v34, v17, v34
	v_mul_f32_e32 v35, 0xbfb8aa3b, v34
	v_fma_f32 v36, v34, s30, -v35
	v_rndne_f32_e32 v37, v35
	v_fmac_f32_e32 v36, 0xb2a5705f, v34
	v_sub_f32_e32 v35, v35, v37
	v_add_f32_e32 v35, v35, v36
	v_exp_f32_e32 v35, v35
	v_cvt_i32_f32_e32 v36, v37
	v_cmp_nlt_f32_e32 vcc, s21, v34
	v_ldexp_f32 v35, v35, v36
	s_nop 0
	v_cndmask_b32_e32 v35, 0, v35, vcc
	v_cmp_ngt_f32_e32 vcc, s23, v34
	s_nop 1
	v_cndmask_b32_e32 v34, v15, v35, vcc
	v_add_f32_e32 v34, 1.0, v34
	v_cmp_gt_f32_e32 vcc, s34, v34
	s_nop 1
	v_cndmask_b32_e64 v35, 0, 32, vcc
	v_ldexp_f32 v34, v34, v35
	v_log_f32_e32 v34, v34
	s_nop 0
	v_mul_f32_e32 v35, 0x3f317217, v34
	v_fma_f32 v35, v34, s35, -v35
	v_fmac_f32_e32 v35, 0x3377d1cf, v34
	v_fmac_f32_e32 v35, 0x3f317217, v34
	v_cmp_lt_f32_e64 s[16:17], |v34|, s31
	s_nop 1
	v_cndmask_b32_e64 v34, v34, v35, s[16:17]
	v_cndmask_b32_e32 v35, 0, v16, vcc
	v_sub_f32_e32 v36, v34, v35
	v_add_co_u32_e32 v34, vcc, s67, v8
	s_nop 1
	v_addc_co_u32_e32 v35, vcc, 0, v9, vcc
	v_mov_b32_e32 v34, v117
	v_lshlrev_b32_e32 v34, 16, v34
	v_add_f32_e32 v34, v17, v34
	v_mul_f32_e32 v35, 0xbfb8aa3b, v34
	v_fma_f32 v37, v34, s30, -v35
	v_rndne_f32_e32 v38, v35
	v_fmac_f32_e32 v37, 0xb2a5705f, v34
	v_sub_f32_e32 v35, v35, v38
	v_add_f32_e32 v35, v35, v37
	v_exp_f32_e32 v35, v35
	v_cvt_i32_f32_e32 v37, v38
	v_cmp_nlt_f32_e32 vcc, s21, v34
	v_ldexp_f32 v35, v35, v37
	s_nop 0
	v_cndmask_b32_e32 v35, 0, v35, vcc
	v_cmp_ngt_f32_e32 vcc, s23, v34
	s_nop 1
	v_cndmask_b32_e32 v34, v15, v35, vcc
	v_add_f32_e32 v34, 1.0, v34
	v_cmp_gt_f32_e32 vcc, s34, v34
	s_nop 1
	v_cndmask_b32_e64 v35, 0, 32, vcc
	v_ldexp_f32 v34, v34, v35
	v_log_f32_e32 v34, v34
	s_nop 0
	v_mul_f32_e32 v35, 0x3f317217, v34
	v_fma_f32 v35, v34, s35, -v35
	v_fmac_f32_e32 v35, 0x3377d1cf, v34
	v_fmac_f32_e32 v35, 0x3f317217, v34
	v_cmp_lt_f32_e64 s[16:17], |v34|, s31
	s_nop 1
	v_cndmask_b32_e64 v34, v34, v35, s[16:17]
	v_cndmask_b32_e32 v35, 0, v16, vcc
	v_sub_f32_e32 v37, v34, v35
	v_add_co_u32_e32 v34, vcc, s68, v8
	s_nop 1
	v_addc_co_u32_e32 v35, vcc, 0, v9, vcc
	v_mov_b32_e32 v34, v118
	v_lshlrev_b32_e32 v34, 16, v34
	v_add_f32_e32 v34, v17, v34
	v_mul_f32_e32 v35, 0xbfb8aa3b, v34
	v_fma_f32 v38, v34, s30, -v35
	v_rndne_f32_e32 v39, v35
	v_fmac_f32_e32 v38, 0xb2a5705f, v34
	v_sub_f32_e32 v35, v35, v39
	v_add_f32_e32 v35, v35, v38
	v_exp_f32_e32 v35, v35
	v_cvt_i32_f32_e32 v38, v39
	v_cmp_nlt_f32_e32 vcc, s21, v34
	v_ldexp_f32 v35, v35, v38
	s_nop 0
	v_cndmask_b32_e32 v35, 0, v35, vcc
	v_cmp_ngt_f32_e32 vcc, s23, v34
	s_nop 1
	v_cndmask_b32_e32 v34, v15, v35, vcc
	v_add_f32_e32 v34, 1.0, v34
	v_cmp_gt_f32_e32 vcc, s34, v34
	s_nop 1
	v_cndmask_b32_e64 v35, 0, 32, vcc
	v_ldexp_f32 v34, v34, v35
	v_log_f32_e32 v34, v34
	s_nop 0
	v_mul_f32_e32 v35, 0x3f317217, v34
	v_fma_f32 v35, v34, s35, -v35
	v_fmac_f32_e32 v35, 0x3377d1cf, v34
	v_fmac_f32_e32 v35, 0x3f317217, v34
	v_cmp_lt_f32_e64 s[16:17], |v34|, s31
	s_nop 1
	v_cndmask_b32_e64 v34, v34, v35, s[16:17]
	v_cndmask_b32_e32 v35, 0, v16, vcc
	v_sub_f32_e32 v38, v34, v35
	v_add_co_u32_e32 v34, vcc, s69, v8
	s_nop 1
	v_addc_co_u32_e32 v35, vcc, 0, v9, vcc
	v_mov_b32_e32 v34, v119
	v_lshlrev_b32_e32 v34, 16, v34
	v_add_f32_e32 v34, v17, v34
	v_mul_f32_e32 v35, 0xbfb8aa3b, v34
	v_fma_f32 v39, v34, s30, -v35
	v_rndne_f32_e32 v40, v35
	v_fmac_f32_e32 v39, 0xb2a5705f, v34
	v_sub_f32_e32 v35, v35, v40
	v_add_f32_e32 v35, v35, v39
	v_exp_f32_e32 v35, v35
	v_cvt_i32_f32_e32 v39, v40
	v_cmp_nlt_f32_e32 vcc, s21, v34
	v_ldexp_f32 v35, v35, v39
	s_nop 0
	v_cndmask_b32_e32 v35, 0, v35, vcc
	v_cmp_ngt_f32_e32 vcc, s23, v34
	s_nop 1
	v_cndmask_b32_e32 v34, v15, v35, vcc
	v_add_f32_e32 v34, 1.0, v34
	v_cmp_gt_f32_e32 vcc, s34, v34
	s_nop 1
	v_cndmask_b32_e64 v35, 0, 32, vcc
	v_ldexp_f32 v34, v34, v35
	v_log_f32_e32 v34, v34
	s_nop 0
	v_mul_f32_e32 v35, 0x3f317217, v34
	v_fma_f32 v35, v34, s35, -v35
	v_fmac_f32_e32 v35, 0x3377d1cf, v34
	v_fmac_f32_e32 v35, 0x3f317217, v34
	v_cmp_lt_f32_e64 s[16:17], |v34|, s31
	s_nop 1
	v_cndmask_b32_e64 v34, v34, v35, s[16:17]
	v_cndmask_b32_e32 v35, 0, v16, vcc
	v_sub_f32_e32 v39, v34, v35
	v_add_co_u32_e32 v34, vcc, s70, v8
	s_nop 1
	v_addc_co_u32_e32 v35, vcc, 0, v9, vcc
	v_mov_b32_e32 v34, v120
	v_lshlrev_b32_e32 v34, 16, v34
	v_add_f32_e32 v34, v17, v34
	v_mul_f32_e32 v35, 0xbfb8aa3b, v34
	v_fma_f32 v40, v34, s30, -v35
	v_rndne_f32_e32 v41, v35
	v_fmac_f32_e32 v40, 0xb2a5705f, v34
	v_sub_f32_e32 v35, v35, v41
	v_add_f32_e32 v35, v35, v40
	v_exp_f32_e32 v35, v35
	v_cvt_i32_f32_e32 v40, v41
	v_cmp_nlt_f32_e32 vcc, s21, v34
	v_ldexp_f32 v35, v35, v40
	s_nop 0
	v_cndmask_b32_e32 v35, 0, v35, vcc
	v_cmp_ngt_f32_e32 vcc, s23, v34
	s_nop 1
	v_cndmask_b32_e32 v34, v15, v35, vcc
	v_add_f32_e32 v34, 1.0, v34
	v_cmp_gt_f32_e32 vcc, s34, v34
	s_nop 1
	v_cndmask_b32_e64 v35, 0, 32, vcc
	v_ldexp_f32 v34, v34, v35
	v_log_f32_e32 v34, v34
	s_nop 0
	v_mul_f32_e32 v35, 0x3f317217, v34
	v_fma_f32 v35, v34, s35, -v35
	v_fmac_f32_e32 v35, 0x3377d1cf, v34
	v_fmac_f32_e32 v35, 0x3f317217, v34
	v_cmp_lt_f32_e64 s[16:17], |v34|, s31
	s_nop 1
	v_cndmask_b32_e64 v34, v34, v35, s[16:17]
	v_cndmask_b32_e32 v35, 0, v16, vcc
	v_sub_f32_e32 v40, v34, v35
	v_add_co_u32_e32 v34, vcc, s71, v8
	s_nop 1
	v_addc_co_u32_e32 v35, vcc, 0, v9, vcc
	v_mov_b32_e32 v34, v121
	v_lshlrev_b32_e32 v34, 16, v34
	v_add_f32_e32 v34, v17, v34
	v_mul_f32_e32 v35, 0xbfb8aa3b, v34
	v_fma_f32 v41, v34, s30, -v35
	v_rndne_f32_e32 v42, v35
	v_fmac_f32_e32 v41, 0xb2a5705f, v34
	v_sub_f32_e32 v35, v35, v42
	v_add_f32_e32 v35, v35, v41
	v_exp_f32_e32 v35, v35
	v_cvt_i32_f32_e32 v41, v42
	v_cmp_nlt_f32_e32 vcc, s21, v34
; __device__ __forceinline__ float bf1(bf16_t h) { return __uint_as_float((unsigned)h << 16); }
; __global__ void __launch_bounds__(512, 2) mega_fwd(Args a) {
;     ...
;         for (int i = 0; i < 32; ++i) { const float f = bf1(PROJ[((size_t)b * SEQ + 32 * lane + i) * NPROJ + PC_FLOG + hh]) + bfg; run += -logf(1.0f + expf(-f)); lf[i] = run; }
	v_ldexp_f32 v35, v35, v41
	s_nop 0
	v_cndmask_b32_e32 v35, 0, v35, vcc
	v_cmp_ngt_f32_e32 vcc, s23, v34
	s_nop 1
	v_cndmask_b32_e32 v34, v15, v35, vcc
	v_add_f32_e32 v34, 1.0, v34
	v_cmp_gt_f32_e32 vcc, s34, v34
	s_nop 1
	v_cndmask_b32_e64 v35, 0, 32, vcc
	v_ldexp_f32 v34, v34, v35
	v_log_f32_e32 v34, v34
	s_nop 0
	v_mul_f32_e32 v35, 0x3f317217, v34
	v_fma_f32 v35, v34, s35, -v35
	v_fmac_f32_e32 v35, 0x3377d1cf, v34
	v_fmac_f32_e32 v35, 0x3f317217, v34
	v_cmp_lt_f32_e64 s[16:17], |v34|, s31
	s_nop 1
	v_cndmask_b32_e64 v34, v34, v35, s[16:17]
	v_cndmask_b32_e32 v35, 0, v16, vcc
	v_sub_f32_e32 v41, v34, v35
	v_add_co_u32_e32 v34, vcc, s72, v8
	s_nop 1
	v_addc_co_u32_e32 v35, vcc, 0, v9, vcc
	v_mov_b32_e32 v34, v122
	v_lshlrev_b32_e32 v34, 16, v34
	v_add_f32_e32 v34, v17, v34
	v_mul_f32_e32 v35, 0xbfb8aa3b, v34
	v_fma_f32 v42, v34, s30, -v35
	v_rndne_f32_e32 v43, v35
	v_fmac_f32_e32 v42, 0xb2a5705f, v34
	v_sub_f32_e32 v35, v35, v43
	v_add_f32_e32 v35, v35, v42
	v_exp_f32_e32 v35, v35
	v_cvt_i32_f32_e32 v42, v43
	v_cmp_nlt_f32_e32 vcc, s21, v34
	v_ldexp_f32 v35, v35, v42
	s_nop 0
	v_cndmask_b32_e32 v35, 0, v35, vcc
	v_cmp_ngt_f32_e32 vcc, s23, v34
	s_nop 1
	v_cndmask_b32_e32 v34, v15, v35, vcc
	v_add_f32_e32 v34, 1.0, v34
	v_cmp_gt_f32_e32 vcc, s34, v34
	s_nop 1
	v_cndmask_b32_e64 v35, 0, 32, vcc
	v_ldexp_f32 v34, v34, v35
	v_log_f32_e32 v34, v34
	s_nop 0
	v_mul_f32_e32 v35, 0x3f317217, v34
	v_fma_f32 v35, v34, s35, -v35
	v_fmac_f32_e32 v35, 0x3377d1cf, v34
	v_fmac_f32_e32 v35, 0x3f317217, v34
	v_cmp_lt_f32_e64 s[16:17], |v34|, s31
	s_nop 1
	v_cndmask_b32_e64 v34, v34, v35, s[16:17]
	v_cndmask_b32_e32 v35, 0, v16, vcc
	v_sub_f32_e32 v42, v34, v35
	v_add_co_u32_e32 v34, vcc, s73, v8
	s_nop 1
	v_addc_co_u32_e32 v35, vcc, 0, v9, vcc
	v_mov_b32_e32 v34, v123
	v_lshlrev_b32_e32 v34, 16, v34
	v_add_f32_e32 v34, v17, v34
	v_mul_f32_e32 v35, 0xbfb8aa3b, v34
	v_fma_f32 v43, v34, s30, -v35
	v_rndne_f32_e32 v44, v35
	v_fmac_f32_e32 v43, 0xb2a5705f, v34
	v_sub_f32_e32 v35, v35, v44
	v_add_f32_e32 v35, v35, v43
	v_exp_f32_e32 v35, v35
	v_cvt_i32_f32_e32 v43, v44
	v_cmp_nlt_f32_e32 vcc, s21, v34
	v_ldexp_f32 v35, v35, v43
	s_nop 0
	v_cndmask_b32_e32 v35, 0, v35, vcc
	v_cmp_ngt_f32_e32 vcc, s23, v34
	s_nop 1
	v_cndmask_b32_e32 v34, v15, v35, vcc
	v_add_f32_e32 v34, 1.0, v34
	v_cmp_gt_f32_e32 vcc, s34, v34
	s_nop 1
	v_cndmask_b32_e64 v35, 0, 32, vcc
	v_ldexp_f32 v34, v34, v35
	v_log_f32_e32 v34, v34
	s_nop 0
	v_mul_f32_e32 v35, 0x3f317217, v34
	v_fma_f32 v35, v34, s35, -v35
	v_fmac_f32_e32 v35, 0x3377d1cf, v34
	v_fmac_f32_e32 v35, 0x3f317217, v34
	v_cmp_lt_f32_e64 s[16:17], |v34|, s31
	s_nop 1
	v_cndmask_b32_e64 v34, v34, v35, s[16:17]
	v_cndmask_b32_e32 v35, 0, v16, vcc
	v_sub_f32_e32 v43, v34, v35
	v_add_co_u32_e32 v34, vcc, s74, v8
	s_nop 1
	v_addc_co_u32_e32 v35, vcc, 0, v9, vcc
	v_mov_b32_e32 v34, v124
	v_lshlrev_b32_e32 v34, 16, v34
	v_add_f32_e32 v34, v17, v34
	v_mul_f32_e32 v35, 0xbfb8aa3b, v34
	v_fma_f32 v44, v34, s30, -v35
	v_rndne_f32_e32 v45, v35
	v_fmac_f32_e32 v44, 0xb2a5705f, v34
	v_sub_f32_e32 v35, v35, v45
	v_add_f32_e32 v35, v35, v44
	v_exp_f32_e32 v35, v35
	v_cvt_i32_f32_e32 v44, v45
	v_cmp_nlt_f32_e32 vcc, s21, v34
	v_ldexp_f32 v35, v35, v44
	s_nop 0
	v_cndmask_b32_e32 v35, 0, v35, vcc
	v_cmp_ngt_f32_e32 vcc, s23, v34
	s_nop 1
	v_cndmask_b32_e32 v34, v15, v35, vcc
	v_add_f32_e32 v34, 1.0, v34
	v_cmp_gt_f32_e32 vcc, s34, v34
	s_nop 1
	v_cndmask_b32_e64 v35, 0, 32, vcc
	v_ldexp_f32 v34, v34, v35
	v_log_f32_e32 v34, v34
	s_nop 0
	v_mul_f32_e32 v35, 0x3f317217, v34
	v_fma_f32 v35, v34, s35, -v35
	v_fmac_f32_e32 v35, 0x3377d1cf, v34
	v_fmac_f32_e32 v35, 0x3f317217, v34
	v_cmp_lt_f32_e64 s[16:17], |v34|, s31
	s_nop 1
	v_cndmask_b32_e64 v34, v34, v35, s[16:17]
	v_cndmask_b32_e32 v35, 0, v16, vcc
	v_sub_f32_e32 v44, v34, v35
	v_add_co_u32_e32 v34, vcc, s75, v8
	s_nop 1
	v_addc_co_u32_e32 v35, vcc, 0, v9, vcc
	v_mov_b32_e32 v34, v125
	v_lshlrev_b32_e32 v34, 16, v34
	v_add_f32_e32 v34, v17, v34
	v_mul_f32_e32 v35, 0xbfb8aa3b, v34
	v_fma_f32 v45, v34, s30, -v35
	v_rndne_f32_e32 v46, v35
	v_fmac_f32_e32 v45, 0xb2a5705f, v34
	v_sub_f32_e32 v35, v35, v46
	v_add_f32_e32 v35, v35, v45
	v_exp_f32_e32 v35, v35
	v_cvt_i32_f32_e32 v45, v46
	v_cmp_nlt_f32_e32 vcc, s21, v34
	v_ldexp_f32 v35, v35, v45
	s_nop 0
	v_cndmask_b32_e32 v35, 0, v35, vcc
	v_cmp_ngt_f32_e32 vcc, s23, v34
	s_nop 1
	v_cndmask_b32_e32 v34, v15, v35, vcc
	v_add_f32_e32 v34, 1.0, v34
	v_cmp_gt_f32_e32 vcc, s34, v34
	s_nop 1
	v_cndmask_b32_e64 v35, 0, 32, vcc
	v_ldexp_f32 v34, v34, v35
	v_log_f32_e32 v34, v34
	s_nop 0
	v_mul_f32_e32 v35, 0x3f317217, v34
	v_fma_f32 v35, v34, s35, -v35
	v_fmac_f32_e32 v35, 0x3377d1cf, v34
	v_fmac_f32_e32 v35, 0x3f317217, v34
	v_cmp_lt_f32_e64 s[16:17], |v34|, s31
	s_nop 1
	v_cndmask_b32_e64 v34, v34, v35, s[16:17]
	v_cndmask_b32_e32 v35, 0, v16, vcc
	v_sub_f32_e32 v45, v34, v35
	v_add_co_u32_e32 v34, vcc, s76, v8
	s_nop 1
	v_addc_co_u32_e32 v35, vcc, 0, v9, vcc
	v_mov_b32_e32 v34, v126
	v_lshlrev_b32_e32 v34, 16, v34
	v_add_f32_e32 v34, v17, v34
	v_mul_f32_e32 v35, 0xbfb8aa3b, v34
	v_fma_f32 v46, v34, s30, -v35
	v_rndne_f32_e32 v47, v35
	v_fmac_f32_e32 v46, 0xb2a5705f, v34
	v_sub_f32_e32 v35, v35, v47
	v_add_f32_e32 v35, v35, v46
	v_exp_f32_e32 v35, v35
	v_cvt_i32_f32_e32 v46, v47
	v_cmp_nlt_f32_e32 vcc, s21, v34
	v_ldexp_f32 v35, v35, v46
	s_nop 0
	v_cndmask_b32_e32 v35, 0, v35, vcc
	v_cmp_ngt_f32_e32 vcc, s23, v34
	s_nop 1
	v_cndmask_b32_e32 v34, v15, v35, vcc
	v_add_f32_e32 v34, 1.0, v34
	v_cmp_gt_f32_e32 vcc, s34, v34
	s_nop 1
	v_cndmask_b32_e64 v35, 0, 32, vcc
	v_ldexp_f32 v34, v34, v35
	v_log_f32_e32 v34, v34
	s_nop 0
	v_mul_f32_e32 v35, 0x3f317217, v34
; __device__ __forceinline__ float bf1(bf16_t h) { return __uint_as_float((unsigned)h << 16); }
; __global__ void __launch_bounds__(512, 2) mega_fwd(Args a) {
;     ...
;         for (int i = 0; i < 32; ++i) { const float f = bf1(PROJ[((size_t)b * SEQ + 32 * lane + i) * NPROJ + PC_FLOG + hh]) + bfg; run += -logf(1.0f + expf(-f)); lf[i] = run; }
;         float incl = run;
; #pragma unroll
;         for (int o = 1; o < 64; o <<= 1) { const float t = __shfl_up(incl, o); if (lane >= o) incl += t; }
	v_fma_f32 v35, v34, s35, -v35
	v_fmac_f32_e32 v35, 0x3377d1cf, v34
	v_fmac_f32_e32 v35, 0x3f317217, v34
	v_cmp_lt_f32_e64 s[16:17], |v34|, s31
	s_nop 1
	v_cndmask_b32_e64 v34, v34, v35, s[16:17]
	v_cndmask_b32_e32 v35, 0, v16, vcc
	v_sub_f32_e32 v46, v34, v35
	v_add_co_u32_e32 v34, vcc, s77, v8
	s_nop 1
	v_addc_co_u32_e32 v35, vcc, 0, v9, vcc
	v_mov_b32_e32 v34, v127
	v_lshlrev_b32_e32 v34, 16, v34
	v_add_f32_e32 v34, v17, v34
	v_mul_f32_e32 v35, 0xbfb8aa3b, v34
	v_fma_f32 v47, v34, s30, -v35
	v_rndne_f32_e32 v48, v35
	v_fmac_f32_e32 v47, 0xb2a5705f, v34
	v_sub_f32_e32 v35, v35, v48
	v_add_f32_e32 v35, v35, v47
	v_exp_f32_e32 v35, v35
	v_cvt_i32_f32_e32 v47, v48
	v_cmp_nlt_f32_e32 vcc, s21, v34
	v_ldexp_f32 v35, v35, v47
	s_nop 0
	v_cndmask_b32_e32 v35, 0, v35, vcc
	v_cmp_ngt_f32_e32 vcc, s23, v34
	s_nop 1
	v_cndmask_b32_e32 v34, v15, v35, vcc
	v_add_f32_e32 v34, 1.0, v34
	v_cmp_gt_f32_e32 vcc, s34, v34
	s_nop 1
	v_cndmask_b32_e64 v35, 0, 32, vcc
	v_ldexp_f32 v34, v34, v35
	v_log_f32_e32 v34, v34
	s_nop 0
	v_mul_f32_e32 v35, 0x3f317217, v34
	v_fma_f32 v35, v34, s35, -v35
	v_fmac_f32_e32 v35, 0x3377d1cf, v34
	v_fmac_f32_e32 v35, 0x3f317217, v34
	v_cmp_lt_f32_e64 s[16:17], |v34|, s31
	s_nop 1
	v_cndmask_b32_e64 v34, v34, v35, s[16:17]
	v_cndmask_b32_e32 v35, 0, v16, vcc
	v_sub_f32_e32 v47, v34, v35
	v_add_co_u32_e32 v34, vcc, s79, v8
	s_nop 1
	v_addc_co_u32_e32 v35, vcc, 0, v9, vcc
	v_mov_b32_e32 v34, v128
	v_lshlrev_b32_e32 v34, 16, v34
	v_add_f32_e32 v34, v17, v34
	v_mul_f32_e32 v35, 0xbfb8aa3b, v34
	v_fma_f32 v48, v34, s30, -v35
	v_rndne_f32_e32 v49, v35
	v_fmac_f32_e32 v48, 0xb2a5705f, v34
	v_sub_f32_e32 v35, v35, v49
	v_add_f32_e32 v35, v35, v48
	v_exp_f32_e32 v35, v35
	v_cvt_i32_f32_e32 v48, v49
	v_cmp_nlt_f32_e32 vcc, s21, v34
	v_ldexp_f32 v35, v35, v48
	s_nop 0
	v_cndmask_b32_e32 v35, 0, v35, vcc
	v_cmp_ngt_f32_e32 vcc, s23, v34
	s_nop 1
	v_cndmask_b32_e32 v34, v15, v35, vcc
	v_add_f32_e32 v34, 1.0, v34
	v_cmp_gt_f32_e32 vcc, s34, v34
	s_nop 1
	v_cndmask_b32_e64 v35, 0, 32, vcc
	v_ldexp_f32 v34, v34, v35
	v_log_f32_e32 v34, v34
	s_nop 0
	v_mul_f32_e32 v35, 0x3f317217, v34
	v_fma_f32 v35, v34, s35, -v35
	v_fmac_f32_e32 v35, 0x3377d1cf, v34
	v_fmac_f32_e32 v35, 0x3f317217, v34
	v_cmp_lt_f32_e64 s[16:17], |v34|, s31
	s_nop 1
	v_cndmask_b32_e64 v34, v34, v35, s[16:17]
	v_cndmask_b32_e32 v35, 0, v16, vcc
	v_sub_f32_e32 v48, v34, v35
	v_add_co_u32_e32 v34, vcc, s80, v8
	s_nop 1
	v_addc_co_u32_e32 v35, vcc, 0, v9, vcc
	v_mov_b32_e32 v34, v129
	v_lshlrev_b32_e32 v34, 16, v34
	v_add_f32_e32 v34, v17, v34
	v_mul_f32_e32 v35, 0xbfb8aa3b, v34
	v_fma_f32 v49, v34, s30, -v35
	v_rndne_f32_e32 v50, v35
	v_fmac_f32_e32 v49, 0xb2a5705f, v34
	v_sub_f32_e32 v35, v35, v50
	v_add_f32_e32 v35, v35, v49
	v_exp_f32_e32 v35, v35
	v_cvt_i32_f32_e32 v49, v50
	v_cmp_nlt_f32_e32 vcc, s21, v34
	v_ldexp_f32 v35, v35, v49
	s_nop 0
	v_cndmask_b32_e32 v35, 0, v35, vcc
	v_cmp_ngt_f32_e32 vcc, s23, v34
	s_nop 1
	v_cndmask_b32_e32 v34, v15, v35, vcc
	v_add_f32_e32 v34, 1.0, v34
	v_cmp_gt_f32_e32 vcc, s34, v34
	s_nop 1
	v_cndmask_b32_e64 v35, 0, 32, vcc
	v_ldexp_f32 v34, v34, v35
	v_log_f32_e32 v34, v34
	s_nop 0
	v_mul_f32_e32 v35, 0x3f317217, v34
	v_fma_f32 v35, v34, s35, -v35
	v_fmac_f32_e32 v35, 0x3377d1cf, v34
	v_fmac_f32_e32 v35, 0x3f317217, v34
	v_cmp_lt_f32_e64 s[16:17], |v34|, s31
	s_nop 1
	v_cndmask_b32_e64 v34, v34, v35, s[16:17]
	v_cndmask_b32_e32 v35, 0, v16, vcc
	v_sub_f32_e32 v49, v34, v35
	v_add_co_u32_e32 v34, vcc, s81, v8
	s_nop 1
	v_addc_co_u32_e32 v35, vcc, 0, v9, vcc
	v_mov_b32_e32 v34, v130
	v_lshlrev_b32_e32 v34, 16, v34
	v_add_f32_e32 v34, v17, v34
	v_mul_f32_e32 v35, 0xbfb8aa3b, v34
	v_fma_f32 v50, v34, s30, -v35
	v_rndne_f32_e32 v51, v35
	v_fmac_f32_e32 v50, 0xb2a5705f, v34
	v_sub_f32_e32 v35, v35, v51
	v_add_f32_e32 v35, v35, v50
	v_exp_f32_e32 v35, v35
	v_cvt_i32_f32_e32 v50, v51
	v_cmp_nlt_f32_e32 vcc, s21, v34
	v_ldexp_f32 v35, v35, v50
	s_nop 0
	v_cndmask_b32_e32 v35, 0, v35, vcc
	v_cmp_ngt_f32_e32 vcc, s23, v34
	s_nop 1
	v_cndmask_b32_e32 v34, v15, v35, vcc
	v_add_f32_e32 v34, 1.0, v34
	v_cmp_gt_f32_e32 vcc, s34, v34
	s_nop 1
	v_cndmask_b32_e64 v35, 0, 32, vcc
	v_ldexp_f32 v34, v34, v35
	v_log_f32_e32 v34, v34
	s_nop 0
	v_mul_f32_e32 v35, 0x3f317217, v34
	v_fma_f32 v35, v34, s35, -v35
	v_fmac_f32_e32 v35, 0x3377d1cf, v34
	v_fmac_f32_e32 v35, 0x3f317217, v34
	v_cmp_lt_f32_e64 s[16:17], |v34|, s31
	s_nop 1
	v_cndmask_b32_e64 v34, v34, v35, s[16:17]
	v_cndmask_b32_e32 v35, 0, v16, vcc
	v_add_co_u32_e32 v8, vcc, s82, v8
	v_sub_f32_e32 v50, v34, v35
	s_nop 0
	v_addc_co_u32_e32 v9, vcc, 0, v9, vcc
	v_mov_b32_e32 v8, v131
	v_lshlrev_b32_e32 v8, 16, v8
	v_add_f32_e32 v8, v17, v8
	v_mul_f32_e32 v9, 0xbfb8aa3b, v8
	v_fma_f32 v17, v8, s30, -v9
	v_rndne_f32_e32 v34, v9
	v_fmac_f32_e32 v17, 0xb2a5705f, v8
	v_sub_f32_e32 v9, v9, v34
	v_add_f32_e32 v9, v9, v17
	v_exp_f32_e32 v9, v9
	v_cvt_i32_f32_e32 v17, v34
	v_cmp_nlt_f32_e32 vcc, s21, v8
	v_ldexp_f32 v9, v9, v17
	s_nop 0
	v_cndmask_b32_e32 v9, 0, v9, vcc
	v_cmp_ngt_f32_e32 vcc, s23, v8
	s_nop 1
	v_cndmask_b32_e32 v8, v15, v9, vcc
	v_add_f32_e32 v8, 1.0, v8
	v_cmp_gt_f32_e32 vcc, s34, v8
	s_nop 1
	v_cndmask_b32_e64 v9, 0, 32, vcc
	v_ldexp_f32 v8, v8, v9
	v_log_f32_e32 v8, v8
	s_nop 0
	v_mul_f32_e32 v9, 0x3f317217, v8
	v_fma_f32 v9, v8, s35, -v9
	v_fmac_f32_e32 v9, 0x3377d1cf, v8
	v_fmac_f32_e32 v9, 0x3f317217, v8
	v_cmp_lt_f32_e64 s[16:17], |v8|, s31
	s_nop 1
	v_cndmask_b32_e64 v8, v8, v9, s[16:17]
	v_cndmask_b32_e32 v9, 0, v16, vcc
	v_sub_f32_e32 v17, v8, v9
	v_sub_f32_e64 v9, -v18, v19
	v_sub_f32_e32 v20, v9, v20
	v_sub_f32_e32 v21, v20, v21
	v_sub_f32_e32 v22, v21, v22
	v_sub_f32_e32 v23, v22, v23
	v_sub_f32_e32 v24, v23, v24
	v_sub_f32_e32 v25, v24, v25
	v_sub_f32_e32 v26, v25, v26
	v_sub_f32_e32 v27, v26, v27
	v_sub_f32_e32 v28, v27, v28
	v_sub_f32_e32 v29, v28, v29
	v_sub_f32_e32 v30, v29, v30
	v_sub_f32_e32 v31, v30, v31
	v_sub_f32_e32 v32, v31, v32
	v_sub_f32_e32 v33, v32, v33
	v_sub_f32_e32 v34, v33, v36
	v_sub_f32_e32 v35, v34, v37
	v_sub_f32_e32 v36, v35, v38
	v_sub_f32_e32 v37, v36, v39
	v_sub_f32_e32 v38, v37, v40
	v_sub_f32_e32 v39, v38, v41
	v_sub_f32_e32 v40, v39, v42
	v_sub_f32_e32 v41, v40, v43
	v_sub_f32_e32 v42, v41, v44
	v_sub_f32_e32 v43, v42, v45
	v_sub_f32_e32 v44, v43, v46
	v_sub_f32_e32 v45, v44, v47
	v_sub_f32_e32 v46, v45, v48
	v_sub_f32_e32 v47, v46, v49
	v_sub_f32_e32 v48, v47, v50
	v_sub_f32_e32 v49, v48, v17
	ds_bpermute_b32 v17, v1, v49
	v_sub_f32_e32 v8, 0, v18
	s_waitcnt lgkmcnt(0)
; __global__ void __launch_bounds__(512, 2) mega_fwd(Args a) {
;     ...
;         for (int o = 1; o < 64; o <<= 1) { const float t = __shfl_up(incl, o); if (lane >= o) incl += t; }
;         const float base = incl - run;
; #pragma unroll
;         for (int i = 0; i < 32; ++i) CL[(size_t)bh * SEQ + 32 * lane + i] = -(base + lf[i]) * LOG2E;
	v_add_f32_e32 v17, v49, v17
	v_cndmask_b32_e64 v17, v17, v49, s[4:5]
	ds_bpermute_b32 v18, v10, v17
	s_waitcnt lgkmcnt(0)
	v_add_f32_e32 v18, v17, v18
	v_cndmask_b32_e64 v17, v18, v17, s[6:7]
	ds_bpermute_b32 v18, v11, v17
	s_waitcnt lgkmcnt(0)
	v_add_f32_e32 v18, v17, v18
	v_cndmask_b32_e64 v17, v18, v17, s[8:9]
	ds_bpermute_b32 v18, v12, v17
	s_waitcnt lgkmcnt(0)
	v_add_f32_e32 v18, v17, v18
	v_cndmask_b32_e64 v17, v18, v17, s[10:11]
	ds_bpermute_b32 v18, v13, v17
	s_waitcnt lgkmcnt(0)
	v_add_f32_e32 v18, v17, v18
	v_cndmask_b32_e64 v17, v18, v17, s[12:13]
	ds_bpermute_b32 v18, v14, v17
	s_waitcnt lgkmcnt(0)
	v_add_f32_e32 v18, v17, v18
	v_cndmask_b32_e64 v17, v18, v17, s[14:15]
	v_sub_f32_e32 v50, v17, v49
	v_pk_add_f32 v[8:9], v[50:51], v[8:9] op_sel_hi:[0,1]
	v_pk_mul_f32 v[18:19], v[8:9], s[30:31] op_sel_hi:[1,0]
	v_pk_add_f32 v[8:9], v[50:51], v[20:21] op_sel_hi:[0,1]
	v_pk_mul_f32 v[20:21], v[8:9], s[30:31] op_sel_hi:[1,0]
	v_pk_add_f32 v[8:9], v[50:51], v[22:23] op_sel_hi:[0,1]
	flat_store_dwordx4 v[4:5], v[18:21]
	s_nop 1
	v_pk_mul_f32 v[18:19], v[8:9], s[30:31] op_sel_hi:[1,0]
	v_pk_add_f32 v[8:9], v[50:51], v[24:25] op_sel_hi:[0,1]
	v_pk_mul_f32 v[20:21], v[8:9], s[30:31] op_sel_hi:[1,0]
	v_pk_add_f32 v[8:9], v[50:51], v[26:27] op_sel_hi:[0,1]
	flat_store_dwordx4 v[4:5], v[18:21] offset:16
	s_nop 1
	v_pk_mul_f32 v[18:19], v[8:9], s[30:31] op_sel_hi:[1,0]
	v_pk_add_f32 v[8:9], v[50:51], v[28:29] op_sel_hi:[0,1]
	v_pk_mul_f32 v[20:21], v[8:9], s[30:31] op_sel_hi:[1,0]
	v_pk_add_f32 v[8:9], v[50:51], v[30:31] op_sel_hi:[0,1]
	flat_store_dwordx4 v[4:5], v[18:21] offset:32
	s_nop 1
	v_pk_mul_f32 v[18:19], v[8:9], s[30:31] op_sel_hi:[1,0]
	v_pk_add_f32 v[8:9], v[50:51], v[32:33] op_sel_hi:[0,1]
	v_pk_mul_f32 v[20:21], v[8:9], s[30:31] op_sel_hi:[1,0]
	v_pk_add_f32 v[8:9], v[50:51], v[34:35] op_sel_hi:[0,1]
	flat_store_dwordx4 v[4:5], v[18:21] offset:48
	s_nop 1
	v_pk_mul_f32 v[18:19], v[8:9], s[30:31] op_sel_hi:[1,0]
	v_pk_add_f32 v[8:9], v[50:51], v[36:37] op_sel_hi:[0,1]
	v_pk_mul_f32 v[20:21], v[8:9], s[30:31] op_sel_hi:[1,0]
	v_pk_add_f32 v[8:9], v[50:51], v[38:39] op_sel_hi:[0,1]
	flat_store_dwordx4 v[4:5], v[18:21] offset:64
	s_nop 1
	v_pk_mul_f32 v[18:19], v[8:9], s[30:31] op_sel_hi:[1,0]
	v_pk_add_f32 v[8:9], v[50:51], v[40:41] op_sel_hi:[0,1]
	v_pk_mul_f32 v[20:21], v[8:9], s[30:31] op_sel_hi:[1,0]
	v_pk_add_f32 v[8:9], v[50:51], v[42:43] op_sel_hi:[0,1]
	flat_store_dwordx4 v[4:5], v[18:21] offset:80
	s_nop 1
	v_pk_mul_f32 v[18:19], v[8:9], s[30:31] op_sel_hi:[1,0]
	v_pk_add_f32 v[8:9], v[50:51], v[44:45] op_sel_hi:[0,1]
	v_pk_mul_f32 v[20:21], v[8:9], s[30:31] op_sel_hi:[1,0]
	v_pk_add_f32 v[8:9], v[50:51], v[46:47] op_sel_hi:[0,1]
	flat_store_dwordx4 v[4:5], v[18:21] offset:96
	s_nop 1
	v_pk_mul_f32 v[18:19], v[8:9], s[30:31] op_sel_hi:[1,0]
	v_pk_add_f32 v[8:9], v[50:51], v[48:49] op_sel_hi:[0,1]
	v_pk_mul_f32 v[20:21], v[8:9], s[30:31] op_sel_hi:[1,0]
	flat_store_dwordx4 v[4:5], v[18:21] offset:112
	v_lshl_add_u64 v[4:5], v[4:5], 0, s[28:29]
	s_cbranch_scc0 .LBB0_892
